# attention next-unit K/V loads: scalar base + one per-lane offset, scalar skip instead of exec masks; SGPR hazard pad restored before Q address
# speedup vs baseline: 1.0048x; 1.0007x over previous
.LBB0_174:
	s_add_i32 s24, s26, s98
	s_cmpk_lt_i32 s24, 0x400
	s_cselect_b64 s[74:75], -1, 0
	s_cmpk_gt_i32 s24, 0x3ff
	s_cselect_b64 s[92:93], -1, 0
	s_and_b64 vcc, exec, s[92:93]
	s_cbranch_vccnz .LBB0_188
	s_and_b32 s21, s24, 15
	v_readlane_b32 s19, v255, 37
	s_lshr_b32 s19, s21, s19
	v_readlane_b32 s27, v255, 1
	s_lshl_b32 s27, s19, s27
	s_sub_i32 s27, s21, s27
	s_lshl_b32 s21, s24, 4
	s_lshl_b32 s34, s27, 8
	s_bfe_u32 s29, s24, 0x40004
	s_and_b32 s31, s21, 0xfffff000
	s_lshl_b32 s21, s29, 6
	s_or_b32 s35, s31, s19
	s_add_i32 s101, s43, 11
	v_lshlrev_b32_e32 v1, s101, v162
	s_add_i32 s100, s101, 8
	v_lshl_add_u32 v1, v164, 1, v1
	s_lshl_b32 s100, s27, s100
	s_lshl_b32 s72, s35, 11
	s_add_i32 s72, s72, s100
	s_lshl_b32 s100, s21, 1
	s_add_i32 s72, s72, s100
	s_add_i32 s100, s101, 6
	s_lshl_b32 s100, 1, s100
	s_add_u32 s72, s4, s72
	s_addc_u32 s73, s5, 0
	global_load_dwordx4 v[90:93], v1, s[72:73]
	s_cmp_eq_u32 s27, 0
	s_cbranch_scc1 .Lk_skip01
	s_sub_u32 s72, s72, s100
	s_subb_u32 s73, s73, 0
	global_load_dwordx4 v[86:89], v1, s[72:73]
	s_sub_u32 s72, s72, s100
	s_subb_u32 s73, s73, 0
	global_load_dwordx4 v[82:85], v1, s[72:73]
	s_add_u32 s72, s72, s100
	s_addc_u32 s73, s73, 0
	s_add_u32 s72, s72, s100
	s_addc_u32 s73, s73, 0
.Lk_skip01:
	s_add_u32 s72, s72, s100
	s_addc_u32 s73, s73, 0
	global_load_dwordx4 v[94:97], v1, s[72:73]
	s_add_u32 s72, s72, s100
	s_addc_u32 s73, s73, 0
	global_load_dwordx4 v[98:101], v1, s[72:73]
	s_add_u32 s72, s72, s100
	s_addc_u32 s73, s73, 0
	global_load_dwordx4 v[102:105], v1, s[72:73]
.LBB0_187:
	v_add_u32_e32 v1, s34, v179
	v_lshlrev_b32_e32 v1, s43, v1
	v_add_lshl_u32 v1, v1, s35, 10
	v_readlane_b32 s34, v255, 3
	v_or3_b32 v130, v1, v166, s21
	v_mov_b32_e32 v131, v0
	v_readlane_b32 s35, v255, 4
	s_nop 1
	v_lshl_add_u64 v[142:143], v[130:131], 1, s[34:35]
	global_load_dwordx4 v[130:133], v[142:143], off
	global_load_dwordx4 v[134:137], v[142:143], off offset:32
	global_load_dwordx4 v[138:141], v[142:143], off offset:64
	s_nop 0
	global_load_dwordx4 v[142:145], v[142:143], off offset:96
	s_branch .LBB0_189

.LBB0_189:
	v_readlane_b32 s34, v255, 11
	v_readlane_b32 s35, v255, 12
	v_cndmask_b32_e64 v1, v50, v232, s[8:9]
	v_cndmask_b32_e64 v58, v58, v232, s[40:41]
	v_cndmask_b32_e64 v50, v66, v232, s[34:35]
	v_readlane_b32 s34, v255, 13
	v_readlane_b32 s35, v255, 14
	v_cndmask_b32_e64 v50, v50, v66, s[8:9]
	v_cndmask_b32_e64 v59, v59, v232, s[44:45]
	v_cndmask_b32_e64 v51, v51, v232, s[34:35]
	v_readlane_b32 s34, v255, 15
	v_readlane_b32 s35, v255, 16
	v_cndmask_b32_e64 v60, v60, v232, s[48:49]
	v_cndmask_b32_e64 v61, v61, v232, s[52:53]
	v_cndmask_b32_e64 v52, v52, v232, s[34:35]
	v_readlane_b32 s34, v255, 17
	v_readlane_b32 s35, v255, 18
	v_cndmask_b32_e64 v62, v62, v232, s[56:57]
	v_cndmask_b32_e64 v63, v63, v232, s[60:61]
	v_cndmask_b32_e64 v66, v68, v232, s[34:35]
	v_readlane_b32 s34, v255, 19
	v_readlane_b32 s35, v255, 20
	v_cndmask_b32_e64 v64, v64, v232, s[64:65]
	v_cndmask_b32_e64 v65, v65, v232, s[68:69]
	v_cndmask_b32_e64 v53, v53, v232, s[34:35]
	v_readlane_b32 s34, v255, 21
	v_readlane_b32 s35, v255, 22
	v_cndmask_b32_e64 v67, v232, v67, s[8:9]
	s_andn2_b64 vcc, exec, s[74:75]
	v_cndmask_b32_e64 v68, v69, v232, s[34:35]
	v_readlane_b32 s34, v255, 23
	v_readlane_b32 s35, v255, 24
	s_nop 1
	v_cndmask_b32_e64 v54, v54, v232, s[34:35]
	v_readlane_b32 s34, v255, 25
	v_readlane_b32 s35, v255, 26
	s_nop 1
	v_cndmask_b32_e64 v69, v70, v232, s[34:35]
	v_readlane_b32 s34, v255, 27
	v_readlane_b32 s35, v255, 28
	s_nop 1
	v_cndmask_b32_e64 v55, v55, v232, s[34:35]
	v_readlane_b32 s34, v255, 29
	v_readlane_b32 s35, v255, 30
	s_nop 1
	v_cndmask_b32_e64 v70, v71, v232, s[34:35]
	v_readlane_b32 s34, v255, 31
	v_readlane_b32 s35, v255, 32
	s_nop 1
	v_cndmask_b32_e64 v56, v56, v232, s[34:35]
	v_readlane_b32 s34, v255, 33
	v_readlane_b32 s35, v255, 34
	s_nop 1
	v_cndmask_b32_e64 v71, v72, v232, s[34:35]
	v_readlane_b32 s34, v255, 35
	v_readlane_b32 s35, v255, 36
	v_cndmask_b32_e64 v72, v73, v232, s[38:39]
	v_cndmask_b32_e64 v73, v74, v232, s[16:17]
	v_cndmask_b32_e64 v57, v57, v232, s[34:35]
	s_mov_b32 s34, 0xf149f2ca
	v_cndmask_b32_e64 v74, v75, v232, s[46:47]
	v_cndmask_b32_e64 v75, v76, v232, s[50:51]
	v_cndmask_b32_e64 v76, v77, v232, s[54:55]
	v_cndmask_b32_e64 v77, v78, v232, s[58:59]
	v_cndmask_b32_e64 v78, v79, v232, s[62:63]
	v_cndmask_b32_e64 v79, v80, v232, s[66:67]
	v_cndmask_b32_e64 v80, v81, v232, s[70:71]
	v_max3_f32 v81, v1, s34, v51
	v_max3_f32 v81, v81, v52, v53
	v_max3_f32 v81, v81, v54, v55
	v_max3_f32 v81, v81, v56, v57
	v_max3_f32 v81, v81, v58, v59
	v_max3_f32 v81, v81, v60, v61
	v_max3_f32 v81, v81, v62, v63
	v_max3_f32 v81, v81, v64, v65
	v_max3_f32 v81, v81, v2, v3
	v_max3_f32 v81, v81, v4, v5
	v_max3_f32 v81, v81, v6, v7
	v_max3_f32 v81, v81, v8, v9
	v_max3_f32 v81, v81, v10, v11
	v_max3_f32 v81, v81, v12, v13
	v_max3_f32 v81, v81, v14, v15
	v_max3_f32 v81, v81, v16, v17
	v_max3_f32 v81, v81, v34, v35
	v_max3_f32 v81, v81, v36, v37
	v_max3_f32 v81, v81, v38, v39
	v_max3_f32 v81, v81, v40, v41
	v_max3_f32 v81, v81, v42, v43
	v_max3_f32 v81, v81, v44, v45
	v_max3_f32 v81, v81, v46, v47
	v_max3_f32 v81, v81, v48, v49
	v_max3_f32 v81, v81, v18, v19
	v_max3_f32 v81, v81, v20, v21
	v_max3_f32 v81, v81, v22, v23
	v_max3_f32 v81, v81, v24, v25
	v_max3_f32 v81, v81, v26, v27
	v_max3_f32 v81, v81, v28, v29
	v_max3_f32 v81, v81, v30, v31
	v_max3_f32 v81, v81, v32, v33
	v_max3_f32 v81, v81, v50, v67
	v_max3_f32 v81, v81, v66, v68
	v_max3_f32 v81, v81, v69, v70
	v_max3_f32 v81, v81, v71, v72
	v_max3_f32 v81, v81, v73, v74
	v_max3_f32 v81, v81, v75, v76
	v_max3_f32 v81, v81, v77, v78
	v_max3_f32 v81, v81, v79, v80
	ds_bpermute_b32 v225, v180, v81
	s_waitcnt lgkmcnt(0)
	v_max_f32_e32 v225, v225, v225
	v_max_f32_e32 v81, v81, v225
	v_sub_f32_e32 v1, v1, v81
	v_exp_f32_e32 v1, v1
	v_sub_f32_e32 v51, v51, v81
	v_exp_f32_e32 v51, v51
	v_sub_f32_e32 v52, v52, v81
	v_exp_f32_e32 v52, v52
	v_sub_f32_e32 v53, v53, v81
	v_exp_f32_e32 v53, v53
	v_sub_f32_e32 v54, v54, v81
	v_add_f32_e32 v225, 0, v1
	v_exp_f32_e32 v54, v54
	v_sub_f32_e32 v55, v55, v81
	v_add_f32_e32 v225, v51, v225
	v_exp_f32_e32 v55, v55
	v_sub_f32_e32 v56, v56, v81
	v_add_f32_e32 v225, v52, v225
	v_exp_f32_e32 v56, v56
	v_sub_f32_e32 v57, v57, v81
	v_add_f32_e32 v225, v53, v225
	v_exp_f32_e32 v57, v57
	v_sub_f32_e32 v58, v58, v81
	v_add_f32_e32 v225, v54, v225
	v_exp_f32_e32 v58, v58
	v_sub_f32_e32 v59, v59, v81
	v_add_f32_e32 v225, v55, v225
	v_exp_f32_e32 v59, v59
	v_sub_f32_e32 v60, v60, v81
	v_add_f32_e32 v225, v56, v225
	v_exp_f32_e32 v60, v60
	v_sub_f32_e32 v61, v61, v81
	v_add_f32_e32 v225, v57, v225
	v_exp_f32_e32 v61, v61
	v_sub_f32_e32 v62, v62, v81
	v_add_f32_e32 v225, v58, v225
	v_exp_f32_e32 v62, v62
	v_sub_f32_e32 v63, v63, v81
	v_add_f32_e32 v225, v59, v225
	v_exp_f32_e32 v63, v63
	v_sub_f32_e32 v64, v64, v81
	v_add_f32_e32 v225, v60, v225
	v_exp_f32_e32 v64, v64
	v_sub_f32_e32 v65, v65, v81
	v_add_f32_e32 v225, v61, v225
	v_exp_f32_e32 v65, v65
	v_sub_f32_e32 v2, v2, v81
	v_add_f32_e32 v225, v62, v225
	v_exp_f32_e32 v230, v2
	v_sub_f32_e32 v2, v3, v81
	v_add_f32_e32 v225, v63, v225
	v_exp_f32_e32 v231, v2
	v_sub_f32_e32 v2, v4, v81
	v_add_f32_e32 v225, v64, v225
	v_exp_f32_e32 v237, v2
	v_sub_f32_e32 v2, v5, v81
	v_add_f32_e32 v225, v65, v225
	v_exp_f32_e32 v238, v2
	v_sub_f32_e32 v3, v6, v81
	v_add_f32_e32 v2, v230, v225
	v_exp_f32_e32 v225, v3
	v_sub_f32_e32 v3, v7, v81
	v_add_f32_e32 v2, v231, v2
	v_exp_f32_e32 v239, v3
	v_sub_f32_e32 v3, v8, v81
	v_add_f32_e32 v2, v237, v2
	v_exp_f32_e32 v240, v3
	v_sub_f32_e32 v3, v9, v81
	v_add_f32_e32 v2, v238, v2
	v_exp_f32_e32 v241, v3
	v_sub_f32_e32 v3, v10, v81
	v_add_f32_e32 v2, v225, v2
	v_exp_f32_e32 v10, v3
	v_sub_f32_e32 v3, v11, v81
	v_add_f32_e32 v2, v239, v2
	v_exp_f32_e32 v11, v3
	v_sub_f32_e32 v3, v12, v81
	v_add_f32_e32 v2, v240, v2
	v_exp_f32_e32 v12, v3
	v_sub_f32_e32 v3, v13, v81
	v_add_f32_e32 v2, v241, v2
	v_exp_f32_e32 v13, v3
	v_sub_f32_e32 v3, v14, v81
	v_add_f32_e32 v2, v10, v2
	v_exp_f32_e32 v14, v3
	v_sub_f32_e32 v3, v15, v81
	v_add_f32_e32 v2, v11, v2
	v_exp_f32_e32 v15, v3
	v_sub_f32_e32 v3, v16, v81
	v_add_f32_e32 v2, v12, v2
	v_exp_f32_e32 v16, v3
	v_sub_f32_e32 v3, v17, v81
	v_add_f32_e32 v2, v13, v2
	v_exp_f32_e32 v17, v3
	v_sub_f32_e32 v3, v34, v81
	v_add_f32_e32 v2, v14, v2
	v_exp_f32_e32 v34, v3
	v_sub_f32_e32 v3, v35, v81
	v_add_f32_e32 v2, v15, v2
	v_exp_f32_e32 v35, v3
	v_sub_f32_e32 v3, v36, v81
	v_add_f32_e32 v2, v16, v2
	v_exp_f32_e32 v36, v3
	v_sub_f32_e32 v3, v37, v81
	v_add_f32_e32 v2, v17, v2
	v_exp_f32_e32 v37, v3
	v_sub_f32_e32 v3, v38, v81
	v_add_f32_e32 v2, v34, v2
	v_exp_f32_e32 v38, v3
	v_sub_f32_e32 v3, v39, v81
	v_add_f32_e32 v2, v35, v2
	v_exp_f32_e32 v39, v3
	v_sub_f32_e32 v3, v40, v81
	v_add_f32_e32 v2, v36, v2
	v_exp_f32_e32 v40, v3
	v_sub_f32_e32 v3, v41, v81
	v_add_f32_e32 v2, v37, v2
	v_exp_f32_e32 v41, v3
	v_sub_f32_e32 v3, v42, v81
	v_add_f32_e32 v2, v38, v2
	v_exp_f32_e32 v42, v3
	v_sub_f32_e32 v3, v43, v81
	v_add_f32_e32 v2, v39, v2
	v_exp_f32_e32 v43, v3
	v_sub_f32_e32 v3, v44, v81
	v_add_f32_e32 v2, v40, v2
	v_exp_f32_e32 v44, v3
	v_sub_f32_e32 v3, v45, v81
	v_add_f32_e32 v2, v41, v2
	v_exp_f32_e32 v45, v3
	v_sub_f32_e32 v3, v46, v81
	v_add_f32_e32 v2, v42, v2
	v_exp_f32_e32 v46, v3
	v_sub_f32_e32 v3, v47, v81
	v_add_f32_e32 v2, v43, v2
	v_exp_f32_e32 v47, v3
	v_sub_f32_e32 v3, v48, v81
	v_add_f32_e32 v2, v44, v2
	v_exp_f32_e32 v48, v3
	v_sub_f32_e32 v3, v49, v81
	v_add_f32_e32 v2, v45, v2
	v_exp_f32_e32 v49, v3
	v_sub_f32_e32 v3, v18, v81
	v_add_f32_e32 v2, v46, v2
	v_exp_f32_e32 v18, v3
	v_sub_f32_e32 v3, v19, v81
	v_add_f32_e32 v2, v47, v2
	v_exp_f32_e32 v19, v3
	v_sub_f32_e32 v3, v20, v81
	v_add_f32_e32 v2, v48, v2
	v_exp_f32_e32 v20, v3
	v_sub_f32_e32 v3, v21, v81
	v_add_f32_e32 v2, v49, v2
	v_exp_f32_e32 v21, v3
	v_sub_f32_e32 v3, v22, v81
	v_add_f32_e32 v2, v18, v2
	v_exp_f32_e32 v22, v3
	v_sub_f32_e32 v3, v23, v81
	v_add_f32_e32 v2, v19, v2
	v_exp_f32_e32 v23, v3
	v_sub_f32_e32 v3, v24, v81
	v_add_f32_e32 v2, v20, v2
	v_exp_f32_e32 v24, v3
	v_sub_f32_e32 v3, v25, v81
	v_add_f32_e32 v2, v21, v2
	v_exp_f32_e32 v25, v3
	v_sub_f32_e32 v3, v26, v81
	v_add_f32_e32 v2, v22, v2
	v_exp_f32_e32 v26, v3
	v_sub_f32_e32 v3, v27, v81
	v_add_f32_e32 v2, v23, v2
	v_exp_f32_e32 v27, v3
	v_sub_f32_e32 v3, v28, v81
	v_add_f32_e32 v2, v24, v2
	v_exp_f32_e32 v28, v3
	v_sub_f32_e32 v3, v29, v81
	v_add_f32_e32 v2, v25, v2
	v_exp_f32_e32 v29, v3
	v_sub_f32_e32 v3, v30, v81
	v_add_f32_e32 v2, v26, v2
	v_exp_f32_e32 v30, v3
	v_sub_f32_e32 v3, v31, v81
	v_add_f32_e32 v2, v27, v2
	v_exp_f32_e32 v31, v3
	v_sub_f32_e32 v3, v32, v81
	v_add_f32_e32 v2, v28, v2
	v_exp_f32_e32 v32, v3
	v_sub_f32_e32 v3, v33, v81
	v_add_f32_e32 v2, v29, v2
	v_exp_f32_e32 v33, v3
	v_sub_f32_e32 v3, v50, v81
	v_add_f32_e32 v2, v30, v2
	v_exp_f32_e32 v50, v3
	v_sub_f32_e32 v3, v67, v81
	v_add_f32_e32 v2, v31, v2
	v_exp_f32_e32 v242, v3
	v_sub_f32_e32 v3, v66, v81
	v_add_f32_e32 v2, v32, v2
	v_exp_f32_e32 v243, v3
	v_sub_f32_e32 v3, v68, v81
	v_add_f32_e32 v2, v33, v2
	v_exp_f32_e32 v244, v3
	v_sub_f32_e32 v3, v69, v81
	v_add_f32_e32 v2, v50, v2
	v_exp_f32_e32 v245, v3
	v_sub_f32_e32 v3, v70, v81
	v_add_f32_e32 v2, v242, v2
	v_exp_f32_e32 v246, v3
	v_sub_f32_e32 v3, v71, v81
	v_add_f32_e32 v2, v243, v2
	v_exp_f32_e32 v247, v3
	v_sub_f32_e32 v3, v72, v81
	v_add_f32_e32 v2, v244, v2
	v_exp_f32_e32 v248, v3
	v_sub_f32_e32 v3, v73, v81
	v_add_f32_e32 v2, v245, v2
	v_exp_f32_e32 v249, v3
	v_sub_f32_e32 v3, v74, v81
	v_add_f32_e32 v2, v246, v2
	v_exp_f32_e32 v250, v3
	v_sub_f32_e32 v3, v75, v81
	v_add_f32_e32 v2, v247, v2
	v_exp_f32_e32 v251, v3
	v_sub_f32_e32 v3, v76, v81
	v_add_f32_e32 v2, v248, v2
	v_exp_f32_e32 v252, v3
	v_sub_f32_e32 v3, v77, v81
	v_add_f32_e32 v2, v249, v2
	v_exp_f32_e32 v253, v3
	v_sub_f32_e32 v3, v78, v81
	v_add_f32_e32 v2, v250, v2
	v_exp_f32_e32 v219, v3
	v_sub_f32_e32 v3, v79, v81
	v_add_f32_e32 v2, v251, v2
	v_exp_f32_e32 v229, v3
	v_sub_f32_e32 v3, v80, v81
	v_add_f32_e32 v2, v252, v2
	v_exp_f32_e32 v80, v3
	v_add_f32_e32 v2, v253, v2
	v_add_f32_e32 v2, v219, v2
	v_add_f32_e32 v2, v229, v2
	v_add_f32_e32 v235, v80, v2
	ds_bpermute_b32 v236, v180, v235
	v_cvt_pk_bf16_f32 v6, v1, v51
	v_cndmask_b32_e64 v1, 0, 1, s[74:75]
	v_cvt_pk_bf16_f32 v7, v52, v53
	v_cvt_pk_bf16_f32 v8, v54, v55
	v_cvt_pk_bf16_f32 v9, v56, v57
	v_cvt_pk_bf16_f32 v2, v58, v59
	v_cvt_pk_bf16_f32 v3, v60, v61
	v_cvt_pk_bf16_f32 v4, v62, v63
	v_cvt_pk_bf16_f32 v5, v64, v65
	v_cvt_pk_bf16_f32 v76, v230, v231
	v_cvt_pk_bf16_f32 v77, v237, v238
	v_cvt_pk_bf16_f32 v78, v225, v239
	v_cvt_pk_bf16_f32 v79, v240, v241
	v_cvt_pk_bf16_f32 v72, v10, v11
	v_cvt_pk_bf16_f32 v73, v12, v13
	v_cvt_pk_bf16_f32 v74, v14, v15
	v_cvt_pk_bf16_f32 v75, v16, v17
	v_cvt_pk_bf16_f32 v68, v34, v35
	v_cvt_pk_bf16_f32 v69, v36, v37
	v_cvt_pk_bf16_f32 v70, v38, v39
	v_cvt_pk_bf16_f32 v71, v40, v41
	v_cvt_pk_bf16_f32 v64, v42, v43
	v_cvt_pk_bf16_f32 v65, v44, v45
	v_cvt_pk_bf16_f32 v66, v46, v47
	v_cvt_pk_bf16_f32 v67, v48, v49
	v_cvt_pk_bf16_f32 v60, v18, v19
	v_cvt_pk_bf16_f32 v61, v20, v21
	v_cvt_pk_bf16_f32 v62, v22, v23
	v_cvt_pk_bf16_f32 v63, v24, v25
	v_cvt_pk_bf16_f32 v56, v26, v27
	v_cvt_pk_bf16_f32 v57, v28, v29
	v_cvt_pk_bf16_f32 v58, v30, v31
	v_cvt_pk_bf16_f32 v59, v32, v33
	v_cvt_pk_bf16_f32 v52, v50, v242
	v_cvt_pk_bf16_f32 v53, v243, v244
	v_cvt_pk_bf16_f32 v54, v245, v246
	v_cvt_pk_bf16_f32 v55, v247, v248
	v_cvt_pk_bf16_f32 v48, v249, v250
	v_cvt_pk_bf16_f32 v49, v251, v252
	v_cvt_pk_bf16_f32 v50, v253, v219
	v_cvt_pk_bf16_f32 v51, v229, v80
	v_cmp_ne_u32_e64 s[72:73], 1, v1
	s_cbranch_vccnz .LBB0_203
	s_add_i32 s101, s43, 11
	v_lshlrev_b32_e32 v10, s101, v162
	s_add_i32 s100, s101, 8
	v_lshl_add_u32 v10, v164, 1, v10
	s_lshl_b32 s100, s27, s100
	s_add_i32 s74, s19, s31
	s_lshl_b32 s74, s74, 11
	s_add_i32 s74, s74, s100
	s_lshl_b32 s100, s21, 1
	s_add_i32 s74, s74, s100
	s_add_i32 s100, s101, 6
	s_lshl_b32 s100, 1, s100
	s_add_u32 s74, s94, s74
	s_addc_u32 s75, s95, 0
	global_load_dwordx4 v[114:117], v10, s[74:75]
	s_cmp_eq_u32 s27, 0
	s_cbranch_scc1 .Lv_skip01
	s_sub_u32 s74, s74, s100
	s_subb_u32 s75, s75, 0
	global_load_dwordx4 v[110:113], v10, s[74:75]
	s_sub_u32 s74, s74, s100
	s_subb_u32 s75, s75, 0
	global_load_dwordx4 v[106:109], v10, s[74:75]
	s_add_u32 s74, s74, s100
	s_addc_u32 s75, s75, 0
	s_add_u32 s74, s74, s100
	s_addc_u32 s75, s75, 0
.Lv_skip01:
	s_add_u32 s74, s74, s100
	s_addc_u32 s75, s75, 0
	global_load_dwordx4 v[118:121], v10, s[74:75]
	s_add_u32 s74, s74, s100
	s_addc_u32 s75, s75, 0
	global_load_dwordx4 v[122:125], v10, s[74:75]
	s_add_u32 s74, s74, s100
	s_addc_u32 s75, s75, 0
	global_load_dwordx4 v[126:129], v10, s[74:75]

.LBB0_568:
	s_nop 1
	ds_read_b32 v130, v238 offset:4608
	v_add_u32_e32 v132, 0x80, v222
	v_ashrrev_i32_e32 v133, 31, v132
	v_lshlrev_b64 v[132:133], 10, v[132:133]
	v_lshl_add_u64 v[134:135], v[132:133], 0, v[220:221]
	s_waitcnt vmcnt(15)
	v_lshlrev_b32_e32 v132, 16, v206
	v_and_b32_e32 v133, 0xffff0000, v206
	v_lshlrev_b32_e32 v136, 16, v207
	v_and_b32_e32 v137, 0xffff0000, v207
	v_lshlrev_b32_e32 v146, 16, v208
	v_and_b32_e32 v147, 0xffff0000, v208
	v_lshlrev_b32_e32 v148, 16, v209
	v_and_b32_e32 v149, 0xffff0000, v209
	s_waitcnt lgkmcnt(0)
	v_pk_mul_f32 v[62:63], v[62:63], v[130:131] op_sel_hi:[1,0]
	v_pk_mul_f32 v[64:65], v[64:65], v[130:131] op_sel_hi:[1,0]
	v_pk_mul_f32 v[58:59], v[58:59], v[130:131] op_sel_hi:[1,0]
	v_pk_mul_f32 v[60:61], v[60:61], v[130:131] op_sel_hi:[1,0]
	v_pk_fma_f32 v[64:65], v[160:161], v[64:65], v[136:137]
	v_pk_fma_f32 v[62:63], v[158:159], v[62:63], v[132:133]
	v_pk_fma_f32 v[60:61], v[156:157], v[60:61], v[148:149]
	v_pk_fma_f32 v[58:59], v[154:155], v[58:59], v[146:147]
	s_mov_b64 s[18:19], -1
	s_and_b64 vcc, exec, s[14:15]
	v_lshl_add_u64 v[132:133], v[134:135], 1, s[16:17]
	s_cbranch_vccz .LBB0_570
	v_cvt_pk_bf16_f32 v146, v62, v63
	v_cvt_pk_bf16_f32 v147, v64, v65
	v_cvt_pk_bf16_f32 v148, v58, v59
	v_cvt_pk_bf16_f32 v149, v60, v61
	s_mov_b64 s[18:19], 0
	global_store_dwordx4 v[132:133], v[146:149], off sc1
	s_nop 1

.LBB0_572:
	v_mov_b32_e32 v131, v130
	v_mov_b32_e32 v164, v130
	v_mov_b32_e32 v165, v130
	s_waitcnt vmcnt(15)
	v_lshlrev_b32_e32 v136, 16, v202
	v_and_b32_e32 v137, 0xffff0000, v202
	v_lshlrev_b32_e32 v146, 16, v203
	v_and_b32_e32 v147, 0xffff0000, v203
	v_lshlrev_b32_e32 v148, 16, v204
	v_and_b32_e32 v149, 0xffff0000, v204
	v_lshlrev_b32_e32 v162, 16, v205
	v_and_b32_e32 v163, 0xffff0000, v205
	v_pk_mul_f32 v[56:57], v[56:57], v[164:165]
	v_pk_mul_f32 v[54:55], v[54:55], v[130:131]
	v_pk_mul_f32 v[52:53], v[52:53], v[164:165]
	v_pk_mul_f32 v[50:51], v[50:51], v[130:131]
	v_pk_fma_f32 v[56:57], v[144:145], v[56:57], v[146:147]
	v_pk_fma_f32 v[54:55], v[142:143], v[54:55], v[136:137]
	v_pk_fma_f32 v[52:53], v[140:141], v[52:53], v[162:163]
	v_pk_fma_f32 v[50:51], v[138:139], v[50:51], v[148:149]
	s_mov_b64 s[18:19], -1
	s_and_b64 vcc, exec, s[14:15]
	s_cbranch_vccz .LBB0_574
	v_cvt_pk_bf16_f32 v146, v54, v55
	v_cvt_pk_bf16_f32 v147, v56, v57
	v_cvt_pk_bf16_f32 v148, v50, v51
	v_cvt_pk_bf16_f32 v149, v52, v53
	v_lshl_add_u64 v[130:131], v[132:133], 0, s[2:3]
	global_store_dwordx4 v[130:131], v[146:149], off sc1
	s_nop 1
	s_mov_b64 s[18:19], 0

.LBB0_576:
	s_nop 1
	ds_read_b32 v130, v238 offset:4672
	v_add_u32_e32 v132, 0x90, v222
	v_ashrrev_i32_e32 v133, 31, v132
	v_lshlrev_b64 v[132:133], 10, v[132:133]
	v_lshl_add_u64 v[134:135], v[132:133], 0, v[220:221]
	s_waitcnt vmcnt(15)
	v_lshlrev_b32_e32 v132, 16, v194
	v_and_b32_e32 v133, 0xffff0000, v194
	v_lshlrev_b32_e32 v136, 16, v195
	v_and_b32_e32 v137, 0xffff0000, v195
	v_lshlrev_b32_e32 v146, 16, v196
	v_and_b32_e32 v147, 0xffff0000, v196
	v_lshlrev_b32_e32 v148, 16, v197
	v_and_b32_e32 v149, 0xffff0000, v197
	s_waitcnt lgkmcnt(0)
	v_pk_mul_f32 v[46:47], v[46:47], v[130:131] op_sel_hi:[1,0]
	v_pk_mul_f32 v[48:49], v[48:49], v[130:131] op_sel_hi:[1,0]
	v_pk_mul_f32 v[42:43], v[42:43], v[130:131] op_sel_hi:[1,0]
	v_pk_mul_f32 v[44:45], v[44:45], v[130:131] op_sel_hi:[1,0]
	v_pk_fma_f32 v[48:49], v[160:161], v[48:49], v[136:137]
	v_pk_fma_f32 v[46:47], v[158:159], v[46:47], v[132:133]
	v_pk_fma_f32 v[44:45], v[156:157], v[44:45], v[148:149]
	v_pk_fma_f32 v[42:43], v[154:155], v[42:43], v[146:147]
	s_mov_b64 s[18:19], -1
	s_and_b64 vcc, exec, s[14:15]
	v_lshl_add_u64 v[132:133], v[134:135], 1, s[16:17]
	s_cbranch_vccz .LBB0_578
	v_cvt_pk_bf16_f32 v146, v46, v47
	v_cvt_pk_bf16_f32 v147, v48, v49
	v_cvt_pk_bf16_f32 v148, v42, v43
	v_cvt_pk_bf16_f32 v149, v44, v45
	s_mov_b64 s[18:19], 0
	global_store_dwordx4 v[132:133], v[146:149], off sc1
	s_nop 1

.LBB0_580:
	v_mov_b32_e32 v131, v130
	v_mov_b32_e32 v164, v130
	v_mov_b32_e32 v165, v130
	s_waitcnt vmcnt(15)
	v_lshlrev_b32_e32 v136, 16, v190
	v_and_b32_e32 v137, 0xffff0000, v190
	v_lshlrev_b32_e32 v146, 16, v191
	v_and_b32_e32 v147, 0xffff0000, v191
	v_lshlrev_b32_e32 v148, 16, v192
	v_and_b32_e32 v149, 0xffff0000, v192
	v_lshlrev_b32_e32 v162, 16, v193
	v_and_b32_e32 v163, 0xffff0000, v193
	v_pk_mul_f32 v[40:41], v[40:41], v[164:165]
	v_pk_mul_f32 v[38:39], v[38:39], v[130:131]
	v_pk_mul_f32 v[36:37], v[36:37], v[164:165]
	v_pk_mul_f32 v[34:35], v[34:35], v[130:131]
	v_pk_fma_f32 v[40:41], v[144:145], v[40:41], v[146:147]
	v_pk_fma_f32 v[38:39], v[142:143], v[38:39], v[136:137]
	v_pk_fma_f32 v[36:37], v[140:141], v[36:37], v[162:163]
	v_pk_fma_f32 v[34:35], v[138:139], v[34:35], v[148:149]
	s_mov_b64 s[18:19], -1
	s_and_b64 vcc, exec, s[14:15]
	s_cbranch_vccz .LBB0_582
	v_cvt_pk_bf16_f32 v146, v38, v39
	v_cvt_pk_bf16_f32 v147, v40, v41
	v_cvt_pk_bf16_f32 v148, v34, v35
	v_cvt_pk_bf16_f32 v149, v36, v37
	v_lshl_add_u64 v[130:131], v[132:133], 0, s[2:3]
	global_store_dwordx4 v[130:131], v[146:149], off sc1
	s_nop 1
	s_mov_b64 s[18:19], 0

.LBB0_584:
	s_nop 1
	ds_read_b32 v130, v238 offset:4736
	v_add_u32_e32 v132, 0xa0, v222
	v_ashrrev_i32_e32 v133, 31, v132
	v_lshlrev_b64 v[132:133], 10, v[132:133]
	v_lshl_add_u64 v[134:135], v[132:133], 0, v[220:221]
	s_waitcnt vmcnt(15)
	v_lshlrev_b32_e32 v132, 16, v182
	v_and_b32_e32 v133, 0xffff0000, v182
	v_lshlrev_b32_e32 v136, 16, v183
	v_and_b32_e32 v137, 0xffff0000, v183
	v_lshlrev_b32_e32 v146, 16, v184
	v_and_b32_e32 v147, 0xffff0000, v184
	v_lshlrev_b32_e32 v148, 16, v185
	v_and_b32_e32 v149, 0xffff0000, v185
	s_waitcnt lgkmcnt(0)
	v_pk_mul_f32 v[30:31], v[30:31], v[130:131] op_sel_hi:[1,0]
	v_pk_mul_f32 v[32:33], v[32:33], v[130:131] op_sel_hi:[1,0]
	v_pk_mul_f32 v[26:27], v[26:27], v[130:131] op_sel_hi:[1,0]
	v_pk_mul_f32 v[28:29], v[28:29], v[130:131] op_sel_hi:[1,0]
	v_pk_fma_f32 v[32:33], v[160:161], v[32:33], v[136:137]
	v_pk_fma_f32 v[30:31], v[158:159], v[30:31], v[132:133]
	v_pk_fma_f32 v[28:29], v[156:157], v[28:29], v[148:149]
	v_pk_fma_f32 v[26:27], v[154:155], v[26:27], v[146:147]
	s_mov_b64 s[18:19], -1
	s_and_b64 vcc, exec, s[14:15]
	v_lshl_add_u64 v[132:133], v[134:135], 1, s[16:17]
	s_cbranch_vccz .LBB0_586
	v_cvt_pk_bf16_f32 v146, v30, v31
	v_cvt_pk_bf16_f32 v147, v32, v33
	v_cvt_pk_bf16_f32 v148, v26, v27
	v_cvt_pk_bf16_f32 v149, v28, v29
	s_mov_b64 s[18:19], 0
	global_store_dwordx4 v[132:133], v[146:149], off sc1
	s_nop 1

.LBB0_588:
	v_mov_b32_e32 v131, v130
	v_mov_b32_e32 v164, v130
	v_mov_b32_e32 v165, v130
	s_waitcnt vmcnt(15)
	v_lshlrev_b32_e32 v136, 16, v174
	v_and_b32_e32 v137, 0xffff0000, v174
	v_lshlrev_b32_e32 v146, 16, v175
	v_and_b32_e32 v147, 0xffff0000, v175
	v_lshlrev_b32_e32 v148, 16, v176
	v_and_b32_e32 v149, 0xffff0000, v176
	v_lshlrev_b32_e32 v162, 16, v177
	v_and_b32_e32 v163, 0xffff0000, v177
	v_pk_mul_f32 v[24:25], v[24:25], v[164:165]
	v_pk_mul_f32 v[22:23], v[22:23], v[130:131]
	v_pk_mul_f32 v[20:21], v[20:21], v[164:165]
	v_pk_mul_f32 v[18:19], v[18:19], v[130:131]
	v_pk_fma_f32 v[24:25], v[144:145], v[24:25], v[146:147]
	v_pk_fma_f32 v[22:23], v[142:143], v[22:23], v[136:137]
	v_pk_fma_f32 v[20:21], v[140:141], v[20:21], v[162:163]
	v_pk_fma_f32 v[18:19], v[138:139], v[18:19], v[148:149]
	s_mov_b64 s[18:19], -1
	s_and_b64 vcc, exec, s[14:15]
	s_cbranch_vccz .LBB0_590
	v_cvt_pk_bf16_f32 v146, v22, v23
	v_cvt_pk_bf16_f32 v147, v24, v25
	v_cvt_pk_bf16_f32 v148, v18, v19
	v_cvt_pk_bf16_f32 v149, v20, v21
	v_lshl_add_u64 v[130:131], v[132:133], 0, s[2:3]
	global_store_dwordx4 v[130:131], v[146:149], off sc1
	s_nop 1
	s_mov_b64 s[18:19], 0

.LBB0_592:
	s_nop 1
	ds_read_b32 v130, v238 offset:4800
	v_add_u32_e32 v132, 0xb0, v222
	v_ashrrev_i32_e32 v133, 31, v132
	v_lshlrev_b64 v[132:133], 10, v[132:133]
	v_lshl_add_u64 v[134:135], v[132:133], 0, v[220:221]
	s_waitcnt vmcnt(15)
	v_lshlrev_b32_e32 v132, 16, v166
	v_and_b32_e32 v133, 0xffff0000, v166
	v_lshlrev_b32_e32 v136, 16, v167
	v_and_b32_e32 v137, 0xffff0000, v167
	v_lshlrev_b32_e32 v146, 16, v168
	v_and_b32_e32 v147, 0xffff0000, v168
	v_lshlrev_b32_e32 v148, 16, v169
	v_and_b32_e32 v149, 0xffff0000, v169
	s_waitcnt lgkmcnt(0)
	v_pk_mul_f32 v[14:15], v[14:15], v[130:131] op_sel_hi:[1,0]
	v_pk_mul_f32 v[16:17], v[16:17], v[130:131] op_sel_hi:[1,0]
	v_pk_mul_f32 v[10:11], v[10:11], v[130:131] op_sel_hi:[1,0]
	v_pk_mul_f32 v[12:13], v[12:13], v[130:131] op_sel_hi:[1,0]
	v_pk_fma_f32 v[16:17], v[160:161], v[16:17], v[136:137]
	v_pk_fma_f32 v[14:15], v[158:159], v[14:15], v[132:133]
	v_pk_fma_f32 v[12:13], v[156:157], v[12:13], v[148:149]
	v_pk_fma_f32 v[10:11], v[154:155], v[10:11], v[146:147]
	s_mov_b64 s[18:19], -1
	s_and_b64 vcc, exec, s[14:15]
	v_lshl_add_u64 v[132:133], v[134:135], 1, s[16:17]
	s_cbranch_vccz .LBB0_594
	v_cvt_pk_bf16_f32 v146, v14, v15
	v_cvt_pk_bf16_f32 v147, v16, v17
	v_cvt_pk_bf16_f32 v148, v10, v11
	v_cvt_pk_bf16_f32 v149, v12, v13
	s_mov_b64 s[18:19], 0
	global_store_dwordx4 v[132:133], v[146:149], off sc1
	s_nop 1

.LBB0_596:
	v_mov_b32_e32 v131, v130
	s_waitcnt vmcnt(15)
	v_lshlrev_b32_e32 v136, 16, v150
	v_and_b32_e32 v137, 0xffff0000, v150
	v_lshlrev_b32_e32 v146, 16, v151
	v_and_b32_e32 v147, 0xffff0000, v151
	v_lshlrev_b32_e32 v148, 16, v152
	v_and_b32_e32 v149, 0xffff0000, v152
	v_lshlrev_b32_e32 v150, 16, v153
	v_and_b32_e32 v151, 0xffff0000, v153
	v_mov_b32_e32 v152, v130
	v_mov_b32_e32 v153, v130
	v_pk_mul_f32 v[8:9], v[8:9], v[152:153]
	v_pk_mul_f32 v[6:7], v[6:7], v[130:131]
	v_pk_mul_f32 v[4:5], v[4:5], v[152:153]
	v_pk_mul_f32 v[2:3], v[2:3], v[130:131]
	v_pk_fma_f32 v[8:9], v[144:145], v[8:9], v[146:147]
	v_pk_fma_f32 v[6:7], v[142:143], v[6:7], v[136:137]
	v_pk_fma_f32 v[4:5], v[140:141], v[4:5], v[150:151]
	v_pk_fma_f32 v[2:3], v[138:139], v[2:3], v[148:149]
	s_mov_b64 s[6:7], -1
	s_and_b64 vcc, exec, s[14:15]
	s_cbranch_vccz .LBB0_598
	v_cvt_pk_bf16_f32 v136, v6, v7
	v_cvt_pk_bf16_f32 v137, v8, v9
	v_cvt_pk_bf16_f32 v138, v2, v3
	v_cvt_pk_bf16_f32 v139, v4, v5
	v_lshl_add_u64 v[130:131], v[132:133], 0, s[2:3]
	global_store_dwordx4 v[130:131], v[136:139], off sc1
	s_nop 1
	s_mov_b64 s[6:7], 0
